# attention: next item's first two K/V chunks (LDS-DMA stage) and sink logit (scalar load) prefetched during the last chunk; prologue reads them back
# baseline (speedup 1.0000x reference)
; __device__ __forceinline__ void attn_mfma(PP p, unsigned char* shm, int wv) {
;     ...
;     for (int item = blockIdx.x; item < 512; item += gridDim.x) {
;         const int hk = item & 1, qb = (item >> 1) & 127, b = item >> 8;
;         const int g = wave >> 1, qh = wave & 1, hq = hk * 4 + g;
;         const int qrow0 = b * S + 128 * qb + 64 * qh;
;         bf16x8 qf[2][4];
; #pragma unroll
;         for (int qi = 0; qi < 2; ++qi)
; #pragma unroll
;             for (int st = 0; st < 4; ++st) qf[qi][st] = *(const bf16x8*)(proj + (size_t)(qrow0 + 32 * qi + l31) * DIN + 1024 + 64 * hq + 16 * st + 8 * hl);
;         const float sink2 = p->attn_sink[hq] * L2E;
;         float mrun[2] = {sink2, sink2};
;         float lrun[2] = {hl == 0 ? 1.f : 0.f, hl == 0 ? 1.f : 0.f};
;         f32x16 oacc[2][2];
; #pragma unroll
;         for (int a = 0; a < 2; ++a)
; #pragma unroll
;             for (int c = 0; c < 2; ++c)
; #pragma unroll
;                 for (int i = 0; i < 16; ++i) oacc[a][c][i] = 0.f;
;         u32x4 kreg[2], vreg[2];
;         int ci = (qb == 0) ? 1 : 0;
.LBB0_456:
	s_and_b32 s14, s34, 1
	s_lshl_b32 s4, s14, 2
	s_add_i32 s16, s4, s27
	s_lshl_b32 s4, s34, 6
	s_bfe_u32 s15, s34, 0x70001
	s_and_b32 s17, s4, 0xffffc000
	s_lshl_b32 s18, s15, 7
	v_or_b32_e32 v1, s17, v180
	v_or_b32_e32 v176, s18, v1
	v_mad_i64_i32 v[2:3], s[4:5], v176, s30, v[168:169]
	s_lshl_b32 s6, s16, 7
	v_or_b32_e32 v174, 32, v176
	v_lshl_add_u64 v[18:19], v[2:3], 0, s[6:7]
	v_mad_i64_i32 v[2:3], s[4:5], v174, s30, v[168:169]
	s_lshl_b32 s4, s16, 2
	v_sub_co_u32_e64 v24, vcc, s15, 1
	v_lshl_add_u64 v[20:21], v[2:3], 0, s[6:7]
	v_mov_b32_e32 v1, s4
	v_addc_co_u32_e64 v2, s[4:5], 0, v24, vcc
	v_lshlrev_b32_e32 v2, 7, v2
	v_add_u32_e32 v12, s17, v2
	v_add_u32_e32 v2, v12, v182
	v_mad_i64_i32 v[2:3], s[4:5], v2, s30, v[168:169]
	s_lshl_b32 s6, s14, 7
	v_lshl_add_u64 v[2:3], v[2:3], 0, s[6:7]
	v_lshl_add_u64 v[10:11], v[2:3], 0, v[172:173]
	s_cmp_eq_u32 s97, 1
	s_cbranch_scc1 .Lattn_pf_sk1
	global_load_dword v1, v1, s[8:9]
	s_nop 0
	global_load_dwordx4 v[2:5], v[10:11], off offset:3072
	global_load_dwordx4 v[6:9], v[10:11], off offset:3328

; __device__ __forceinline__ void attn_mfma(PP p, unsigned char* shm, int wv) {
;     ...
;         bf16x8 qf[2][4];
; #pragma unroll
;         for (int qi = 0; qi < 2; ++qi)
; #pragma unroll
;             for (int st = 0; st < 4; ++st) qf[qi][st] = *(const bf16x8*)(proj + (size_t)(qrow0 + 32 * qi + l31) * DIN + 1024 + 64 * hq + 16 * st + 8 * hl);
;         const float sink2 = p->attn_sink[hq] * L2E;
;         float mrun[2] = {sink2, sink2};
;         float lrun[2] = {hl == 0 ? 1.f : 0.f, hl == 0 ? 1.f : 0.f};
;         f32x16 oacc[2][2];
; #pragma unroll
;         for (int a = 0; a < 2; ++a)
; #pragma unroll
;             for (int c = 0; c < 2; ++c)
; #pragma unroll
;                 for (int i = 0; i < 16; ++i) oacc[a][c][i] = 0.f;
;         u32x4 kreg[2], vreg[2];
;         int ci = (qb == 0) ? 1 : 0;
;     ...
;         ATT_GLOAD(ci);
;         __syncthreads();
;         ATT_STAGE(0);
;         { const int c1 = ATT_NEXT(ci); if (c1 < 5) ATT_GLOAD(c1); }
;         __syncthreads();
.Lattn_pf_sk2:
	global_load_dwordx4 v[82:85], v[18:19], off offset:2048
	global_load_dwordx4 v[86:89], v[18:19], off offset:2080
	global_load_dwordx4 v[90:93], v[18:19], off offset:2112
	global_load_dwordx4 v[94:97], v[18:19], off offset:2144
	v_lshl_add_u64 v[18:19], v[20:21], 0, v[170:171]
	global_load_dwordx4 v[98:101], v[18:19], off offset:2048
	global_load_dwordx4 v[102:105], v[18:19], off offset:2080
	global_load_dwordx4 v[106:109], v[18:19], off offset:2112
	global_load_dwordx4 v[110:113], v[18:19], off offset:2144
	v_add_u32_e32 v18, s4, v24
	v_lshlrev_b32_e32 v18, 7, v18
	v_add_u32_e32 v20, s17, v18
	v_add_u32_e32 v18, v20, v182
	v_mad_i64_i32 v[18:19], s[4:5], v18, s30, v[168:169]
	v_lshl_add_u64 v[18:19], v[18:19], 0, s[6:7]
	v_lshl_add_u64 v[18:19], v[18:19], 0, v[172:173]
	s_waitcnt vmcnt(63) expcnt(7) lgkmcnt(15)
	s_barrier
	s_cmp_eq_u32 s97, 1
	s_cbranch_scc1 .Lattn_pf_sk3
	global_load_dwordx4 v[114:117], v[18:19], off offset:3072
	global_load_dwordx4 v[118:121], v[18:19], off offset:3328
.Lattn_pf_sk3:
	v_add_u32_e32 v18, v20, v183
	v_mad_i64_i32 v[18:19], s[4:5], v18, s30, v[168:169]
	v_lshl_add_u64 v[18:19], v[18:19], 0, s[6:7]
	v_lshl_add_u64 v[18:19], v[18:19], 0, v[172:173]
	s_cmp_eq_u32 s97, 1
	s_cbranch_scc1 .Lattn_pf_sk4
	global_load_dwordx4 v[122:125], v[18:19], off offset:3072
	global_load_dwordx4 v[126:129], v[18:19], off offset:3328
.Lattn_pf_sk4:
	v_cndmask_b32_e64 v25, 0, 1, vcc
	s_cmpk_eq_i32 s15, 0x7f
	v_readfirstlane_b32 s38, v25
	s_cselect_b64 s[4:5], -1, 0
	s_and_b32 s36, s34, 0xffffff00
	s_or_b32 s37, s18, s17
	v_ashrrev_i32_e32 v177, 31, v176
	v_ashrrev_i32_e32 v175, 31, v174
	s_addk_i32 s36, 0x7e80
	s_addk_i32 s37, 0x80
	v_lshl_add_u64 v[178:179], v[166:167], 0, s[6:7]
	v_mov_b32_e32 v196, v163
	s_mov_b32 s6, 0
	s_waitcnt vmcnt(15)
	s_cmp_eq_u32 s97, 1
	s_cbranch_scc0 .Lattn_pf_norb
	s_mov_b32 s97, 0
	v_mov_b32_e32 v1, s100
	s_lshl_b32 s98, s33, 6
	s_add_i32 s98, s98, 0x12000
	v_lshlrev_b32_e32 v66, 4, v195
	v_add_u32_e32 v66, s98, v66
	ds_read_b128 v[2:5], v66
	ds_read_b128 v[6:9], v66 offset:1024
	ds_read_b128 v[10:13], v66 offset:2048
	ds_read_b128 v[14:17], v66 offset:3072
	ds_read_b128 v[114:117], v66 offset:32768
	ds_read_b128 v[118:121], v66 offset:33792
	ds_read_b128 v[122:125], v66 offset:34816
	ds_read_b128 v[126:129], v66 offset:35840
	s_waitcnt lgkmcnt(0)

; __device__ __forceinline__ void attn_mfma(PP p, unsigned char* shm, int wv) {
;     ...
;         const float sink2 = p->attn_sink[hq] * L2E;
;     ...
;         while (ci < 5) {
;             const int cn = ATT_NEXT(ci);
;             if (cn < 5) { ATT_STAGE(par ^ 1); const int c2 = ATT_NEXT(cn); if (c2 < 5) ATT_GLOAD(c2); }
;             const bf16_t* Ks = (const bf16_t*)(shm + par * 36864);
;             const bf16_t* Vt = (const bf16_t*)(shm + par * 36864 + 18432);
;             const int kt_lo = (ci == 0 && qh == 1) ? 2 : 0, kt_hi = (ci == 2 && qh == 0) ? 2 : 4;
; #pragma unroll 1
;             for (int kt = kt_lo; kt < kt_hi; ++kt) {
.LBB0_460:
	s_cmp_eq_u32 s38, 0
	s_cselect_b64 s[16:17], -1, 0
	s_cmp_lg_u32 s38, 0
	s_cselect_b64 s[18:19], -1, 0
	s_and_b64 s[20:21], s[10:11], s[16:17]
	s_and_b64 s[20:21], s[20:21], exec
	s_cselect_b32 s40, 2, 0
	s_cmp_eq_u32 s38, 2
	s_cselect_b64 s[20:21], -1, 0
	s_and_b64 s[20:21], s[12:13], s[20:21]
	s_and_b64 s[20:21], s[20:21], exec
	s_cselect_b32 s41, 2, 4
	s_cmp_ge_u32 s40, s41
	s_cbranch_scc1 .LBB0_487
	s_mul_i32 s20, s6, 0x9000
	s_lshl_b32 s21, s40, 6
	s_or_b32 s21, s20, s21
	v_add_u32_e32 v199, s21, v187
	s_mul_i32 s21, s40, 0x1200
	s_add_i32 s20, s20, s21
	v_add_u32_e32 v200, s20, v188
	v_lshl_add_u32 v201, s40, 5, v189
	s_cmp_eq_u32 s38, 0
	s_cbranch_scc1 .Lattn_p_entry_m0
	s_cmp_eq_u32 s38, 2
	s_cbranch_scc1 .Lattn_p_entry_m2
	s_cmp_lg_u32 s38, 4
	s_cbranch_scc1 .Lattn_p_entry_u
	s_add_i32 s98, s34, s24
	s_cmpk_gt_i32 s98, 0x1ff
	s_cbranch_scc1 .Lattn_p_entry_u
	s_bfe_u32 s100, s98, 0x70001
	s_add_i32 s100, s100, -1
	s_max_i32 s100, s100, 0
	s_lshl_b32 s100, s100, 7
	s_lshl_b32 s101, s98, 6
	s_and_b32 s101, s101, 0xffffc000
	s_add_i32 s100, s100, s101
	s_and_b32 s98, s98, 1
	s_lshl_b32 s98, s98, 7
	s_addk_i32 s98, 0xc00
	s_mov_b32 s99, 0
	v_add_u32_e32 v220, s100, v182
	v_add_u32_e32 v221, s100, v183
	v_mad_i64_i32 v[222:223], s[100:101], v220, s30, v[168:169]
	v_mad_i64_i32 v[226:227], s[100:101], v221, s30, v[168:169]
	v_lshl_add_u64 v[222:223], v[222:223], 0, v[172:173]
	v_lshl_add_u64 v[226:227], v[226:227], 0, v[172:173]
	v_lshl_add_u64 v[222:223], v[222:223], 0, s[98:99]
	v_lshl_add_u64 v[226:227], v[226:227], 0, s[98:99]
	s_movk_i32 s98, 0x100
	v_lshl_add_u64 v[224:225], v[222:223], 0, s[98:99]
	v_lshl_add_u64 v[228:229], v[226:227], 0, s[98:99]
	s_lshl_b32 s101, s33, 6
	s_add_i32 s101, s101, 0x12000
	s_mov_b32 m0, s101
	s_nop 0
	global_load_lds_dwordx4 v[222:223], off
	s_add_i32 m0, s101, 0x400
	s_nop 0
	global_load_lds_dwordx4 v[224:225], off
	s_add_i32 m0, s101, 0x800
	s_nop 0
	global_load_lds_dwordx4 v[226:227], off
	s_add_i32 m0, s101, 0xc00
	s_nop 0
	global_load_lds_dwordx4 v[228:229], off
	s_mov_b32 s98, 0x70000
	v_lshl_add_u64 v[222:223], v[222:223], 0, s[98:99]
	v_lshl_add_u64 v[224:225], v[224:225], 0, s[98:99]
	v_lshl_add_u64 v[226:227], v[226:227], 0, s[98:99]
	v_lshl_add_u64 v[228:229], v[228:229], 0, s[98:99]
	s_add_i32 m0, s101, 0x8000
	s_nop 0
	global_load_lds_dwordx4 v[222:223], off
	s_add_i32 m0, s101, 0x8400
	s_nop 0
	global_load_lds_dwordx4 v[224:225], off
	s_add_i32 m0, s101, 0x8800
	s_nop 0
	global_load_lds_dwordx4 v[226:227], off
	s_add_i32 m0, s101, 0x8c00
	s_nop 0
	global_load_lds_dwordx4 v[228:229], off
	s_add_i32 s100, s34, s24
	s_and_b32 s100, s100, 1
	s_lshl_b32 s100, s100, 2
	s_add_i32 s100, s100, s27
	s_lshl_b32 s100, s100, 2
	s_load_dword s100, s[8:9], s100
	s_waitcnt lgkmcnt(0)
	s_mov_b32 s97, 1
	s_branch .Lattn_p_entry_u
